# block-id permutation (all batches on every XCD) + batch-asymmetric P0: every WG converts its 2 w_in tiles first (CW_W), later-GEMM weight tiles split 0/2/4/5 per batch so batches enter GEMM1 de-phased
# speedup vs baseline: 1.0328x; 1.0328x over previous
_Z7hyb_fwd4Args:
	s_mov_b32 s100, 0
	s_and_b32 s3, s2, 7
	s_lshl_b32 s3, s3, 3
	s_bfe_u32 s4, s2, 0x30003
	s_or_b32 s3, s3, s4
	s_andn2_b32 s2, s2, 63
	s_or_b32 s2, s2, s3
	s_load_dword s58, s[0:1], 0xa0
	v_readfirstlane_b32 s96, v0
	s_mov_b32 s83, s2
	s_waitcnt lgkmcnt(0)
	s_and_b32 s3, s58, 7
	s_cmp_lg_u32 s3, 0
	s_cbranch_scc1 .LBB0_2
	s_ashr_i32 s4, s2, 31
	s_lshr_b32 s4, s4, 29
	s_add_i32 s4, s2, s4
	s_and_b32 s5, s4, -8
	s_ashr_i32 s3, s58, 3
	s_sub_i32 s5, s2, s5
	s_mul_i32 s3, s3, s5
	s_ashr_i32 s4, s4, 3
	s_add_i32 s83, s3, s4

.LBB0_34:
	s_cmp_lg_u32 s100, 0
	s_cbranch_scc1 .Lp0_go
	s_lshl_b32 s8, s83, 1
	s_add_i32 s10, s8, 2

.LBB0_152:
	s_waitcnt vmcnt(0)
	v_cmp_eq_u32_e32 vcc, 0, v90
	s_waitcnt vmcnt(0)
	s_barrier
	s_cmp_lg_u32 s100, 0
	s_cbranch_scc1 .Lp0_second_done
	s_and_saveexec_b64 s[0:1], vcc
	s_cbranch_execz .LBB0_155
	s_mov_b64 s[4:5], exec
	v_mbcnt_lo_u32_b32 v0, s4, 0
	v_mbcnt_hi_u32_b32 v0, s5, v0
	v_cmp_eq_u32_e32 vcc, 0, v0
	s_and_b64 s[6:7], exec, vcc
	s_mov_b64 exec, s[6:7]
	s_cbranch_execz .LBB0_155
	s_bcnt1_i32_b64 s3, s[4:5]
	v_mov_b32_e32 v0, 0x8000
	v_mov_b32_e32 v1, s3
	global_atomic_add v0, v1, s[54:55] offset:512
.LBB0_155:
	s_or_b64 exec, exec, s[0:1]
	s_mov_b32 s100, 1
	s_lshr_b32 s0, s83, 6
	s_and_b32 s1, s83, 63
	s_movk_i32 s4, 0
	s_movk_i32 s5, 512
	s_cmp_eq_u32 s0, 1
	s_cselect_b32 s4, 2, s4
	s_cselect_b32 s5, 512, s5
	s_cmp_eq_u32 s0, 2
	s_cselect_b32 s4, 4, s4
	s_cselect_b32 s5, 640, s5
	s_cmp_eq_u32 s0, 3
	s_cselect_b32 s4, 5, s4
	s_cselect_b32 s5, 896, s5
	s_cmp_eq_u32 s4, 0
	s_cbranch_scc1 .Lp0_second_done
	s_mul_i32 s6, s1, s4
	s_add_i32 s8, s5, s6
	s_add_i32 s10, s8, s4
	s_mul_i32 s3, s62, 0x2080
	s_mov_b32 s33, s3
	s_branch .LBB0_34
.Lp0_second_done:
.LBB0_156:
	s_cmp_lt_i32 s68, 2
	s_cselect_b64 s[0:1], -1, 0
	s_cmp_gt_i32 s69, 1
	s_cselect_b64 s[4:5], -1, 0
	s_and_b64 s[18:19], s[0:1], s[4:5]
	s_andn2_b64 vcc, exec, s[18:19]
	s_cbranch_vccnz .LBB0_185
	v_mbcnt_lo_u32_b32 v20, -1, 0
	v_mbcnt_hi_u32_b32 v20, -1, v20
	s_nop 0
	v_or_b32_e32 v0, s62, v20
	v_cmp_eq_u32_e32 vcc, 0, v0
	s_and_saveexec_b64 s[0:1], vcc
	s_cbranch_execz .LBB0_172
	v_mov_b32_e32 v0, 0x8000
	global_load_dword v0, v0, s[54:55] sc1
	s_movk_i32 s3, 0xff
	s_add_u32 s6, s54, 0x8000
	s_addc_u32 s7, s55, 0
	s_waitcnt vmcnt(0)
	v_cmp_lt_u32_e32 vcc, s3, v0
	s_cbranch_vccnz .LBB0_171
	s_add_u32 s4, s54, 0x4200
	s_addc_u32 s5, s55, 0
	s_mov_b32 s14, 1
	v_mov_b32_e32 v0, 0
	s_branch .LBB0_161
